# residual-GEMM phases walk their tile ids in reverse (id xor 1023) so they read the most recently written rows of the previous phase first
# speedup vs baseline: 1.0226x; 1.0075x over previous
; DI void phase_gemm_resid(const bf16_t* __restrict__ A, int K, const bf16_t* __restrict__ Bt, const float* __restrict__ xin, float* __restrict__ xout, float alpha, unsigned char* smem) {
;     ...
;   for (int id = blockIdx.x; id < nM * nN; id += gridDim.x) {
;     int pm, pn; tile_coords(id, nN, pm, pn);
;     f32x4 acc[8][4]; zero_acc(acc);
;     {
;       const int idn = id + gridDim.x; int pm2 = 0, pn2 = 0; const bool hn = idn < nM * nN; if (hn) tile_coords(idn, nN, pm2, pn2);
;       gemm_block<8, 4, 2, 4>(A + (size_t)pm * 256 * K, K, Bt + (size_t)pn * 256 * K, K, K, acc, smem, id != (int)blockIdx.x,
;                              hn ? A + (size_t)pm2 * 256 * K : nullptr, K, Bt + (size_t)pn2 * 256 * K, K);
.LBB0_195:
	v_readlane_b32 s12, v252, 0
	v_readlane_b32 s14, v252, 2
	s_add_i32 s22, s2, s14
	s_cmpk_gt_i32 s22, 0x3ff
	v_readlane_b32 s13, v252, 1
	s_cselect_b64 s[38:39], -1, 0
	s_cmpk_lt_i32 s22, 0x400
	s_cselect_b64 s[12:13], -1, 0
	s_mov_b64 s[10:11], 0
	s_and_b64 vcc, exec, s[38:39]
	s_mov_b64 s[42:43], 0
	v_readlane_b32 s15, v252, 3
	s_cbranch_vccnz .LBB0_197
	s_xor_b32 s99, s22, 0x3ff
	s_ashr_i32 s6, s99, 31
	s_lshr_b32 s6, s6, 26
	s_add_i32 s6, s99, s6
	s_ashr_i32 s7, s6, 6
	s_andn2_b32 s6, s6, 63
	s_sub_i32 s6, s99, s6
	s_lshl_b32 s7, s7, 4
	s_and_b32 s10, s6, 15
	s_lshr_b32 s6, s6, 4
	s_or_b32 s7, s10, s7
	s_mul_i32 s42, s6, 0xb0000
	s_mul_hi_i32 s11, s7, 0xb0000
	s_mul_i32 s10, s7, 0xb0000
	s_ashr_i32 s43, s42, 31

; DI void glds16(const void* g, unsigned char* l) { __builtin_amdgcn_global_load_lds((const unsigned*)g, (lds_u32*)l, 16, 0, 0); }
;     ...
;   const int srow = tid >> 3, kch = (tid & 7) ^ ((tid >> 4) & 7);
;   const unsigned voA = (unsigned)(srow * lda + kch * 8) * 2u, voB = (unsigned)(srow * ldb + kch * 8) * 2u;
;   const char* Ab = (const char*)A;
;   const char* Bb = (const char*)B;
;   const int nk = K >> 6;
;   if (!primed) {
; #pragma unroll
;     for (int i = 0; i < NA; ++i) glds16(Ab + (size_t)i * 128 * lda + voA, smem + (i * 512 + tid) * 16);
; #pragma unroll
;     for (int i = 0; i < NB; ++i) glds16(Bb + (size_t)i * 128 * ldb + voB, smem + AB + (i * 512 + tid) * 16);
;   }
; DI void phase_gemm_resid(const bf16_t* __restrict__ A, int K, const bf16_t* __restrict__ Bt, const float* __restrict__ xin, float* __restrict__ xout, float alpha, unsigned char* smem) {
;     ...
;   for (int id = blockIdx.x; id < nM * nN; id += gridDim.x) {
;     int pm, pn; tile_coords(id, nN, pm, pn);
;     f32x4 acc[8][4]; zero_acc(acc);
;     {
;       const int idn = id + gridDim.x; int pm2 = 0, pn2 = 0; const bool hn = idn < nM * nN; if (hn) tile_coords(idn, nN, pm2, pn2);
;       gemm_block<8, 4, 2, 4>(A + (size_t)pm * 256 * K, K, Bt + (size_t)pn * 256 * K, K, K, acc, smem, id != (int)blockIdx.x,
;                              hn ? A + (size_t)pm2 * 256 * K : nullptr, K, Bt + (size_t)pn2 * 256 * K, K);
.LBB0_199:
	s_xor_b32 s99, s2, 0x3ff
	s_ashr_i32 s6, s99, 31
	s_lshr_b32 s6, s6, 26
	s_add_i32 s6, s99, s6
	s_ashr_i32 s7, s6, 6
	s_andn2_b32 s6, s6, 63
	v_lshrrev_b32_e32 v4, 4, v0
	s_sub_i32 s2, s99, s6
	v_ashrrev_i32_e32 v2, 3, v0
	v_xor_b32_e32 v3, v4, v0
	s_movk_i32 s27, 0xb00
	s_lshl_b32 s23, s7, 4
	s_and_b32 s26, s2, 15
	s_ashr_i32 s2, s2, 4
	v_mul_lo_u32 v5, v2, s27
	v_lshlrev_b32_e32 v6, 3, v3
	s_or_b32 s6, s26, s23
	s_mul_i32 s14, s2, 0xb0000
	v_and_or_b32 v5, v6, 56, v5
	s_ashr_i32 s7, s6, 31
	s_ashr_i32 s15, s14, 31
	s_andn2_b64 vcc, exec, s[16:17]
	v_lshlrev_b32_e32 v128, 1, v5
	s_cbranch_vccnz .LBB0_201
	s_mul_i32 s16, s6, 0x160000
	s_mul_hi_i32 s17, s6, 0x160000
	s_add_u32 s16, s52, s16
	s_addc_u32 s17, s53, s17
	v_lshl_add_u64 v[6:7], s[16:17], 0, v[128:129]
	v_readfirstlane_b32 s16, v1
	v_add_u32_e32 v5, 0x2000, v1
	s_mov_b32 m0, s16
	s_mov_b64 s[46:47], 0x58000
	v_readfirstlane_b32 s16, v5
	v_add_u32_e32 v5, 0x4000, v1
	s_lshl_b64 s[44:45], s[14:15], 1
	global_load_lds_dwordx4 v[6:7], off
	v_lshl_add_u64 v[8:9], v[6:7], 0, s[46:47]
	s_mov_b32 m0, s16
	s_mov_b64 s[90:91], 0xb0000
	v_readfirstlane_b32 s16, v5
	v_add_u32_e32 v5, 0x6000, v1
	s_add_u32 s44, s18, s44
	global_load_lds_dwordx4 v[8:9], off
	v_lshl_add_u64 v[8:9], v[6:7], 0, s[90:91]
	s_mov_b32 m0, s16
	s_mov_b64 vcc, 0x108000
	v_readfirstlane_b32 s16, v5
	v_add_u32_e32 v5, 0x8000, v1
	s_addc_u32 s45, s19, s45
	global_load_lds_dwordx4 v[8:9], off
	v_lshl_add_u64 v[6:7], v[6:7], 0, vcc
	s_mov_b32 m0, s16
	v_readfirstlane_b32 s16, v5
	v_add_u32_e32 v5, 0xa000, v1
	global_load_lds_dwordx4 v[6:7], off
	v_lshl_add_u64 v[6:7], s[44:45], 0, v[128:129]
	s_mov_b32 m0, s16
	v_readfirstlane_b32 s16, v5
	v_add_u32_e32 v5, 0xc000, v1
	global_load_lds_dwordx4 v[6:7], off
	v_lshl_add_u64 v[8:9], v[6:7], 0, s[46:47]
	s_mov_b32 m0, s16
	v_readfirstlane_b32 s16, v5
	v_add_u32_e32 v5, 0xe000, v1
	global_load_lds_dwordx4 v[8:9], off
	v_lshl_add_u64 v[8:9], v[6:7], 0, s[90:91]
	s_mov_b32 m0, s16
	v_readfirstlane_b32 s16, v5
	global_load_lds_dwordx4 v[8:9], off
	v_lshl_add_u64 v[6:7], v[6:7], 0, vcc
	s_mov_b32 m0, s16
	v_mov_b32_e32 v133, v1
	global_load_lds_dwordx4 v[6:7], off

; DI void phase_gemm_resid(const bf16_t* __restrict__ A, int K, const bf16_t* __restrict__ Bt, const float* __restrict__ xin, float* __restrict__ xout, float alpha, unsigned char* smem) {
;     ...
;   for (int id = blockIdx.x; id < nM * nN; id += gridDim.x) {
;     int pm, pn; tile_coords(id, nN, pm, pn);
;     f32x4 acc[8][4]; zero_acc(acc);
;     {
;       const int idn = id + gridDim.x; int pm2 = 0, pn2 = 0; const bool hn = idn < nM * nN; if (hn) tile_coords(idn, nN, pm2, pn2);
;       gemm_block<8, 4, 2, 4>(A + (size_t)pm * 256 * K, K, Bt + (size_t)pn * 256 * K, K, K, acc, smem, id != (int)blockIdx.x,
;                              hn ? A + (size_t)pm2 * 256 * K : nullptr, K, Bt + (size_t)pn2 * 256 * K, K);
.LBB0_760:
	v_readlane_b32 s4, v252, 0
	v_readlane_b32 s6, v252, 2
	s_add_i32 s21, s2, s6
	s_cmpk_gt_i32 s21, 0x3ff
	s_cselect_b64 s[0:1], -1, 0
	s_cmpk_lt_i32 s21, 0x400
	s_cselect_b64 s[12:13], -1, 0
	s_mov_b64 s[10:11], 0
	s_and_b64 vcc, exec, s[0:1]
	s_mov_b64 s[38:39], 0
	v_readlane_b32 s5, v252, 1
	v_readlane_b32 s7, v252, 3
	s_cbranch_vccnz .LBB0_762
	s_xor_b32 s99, s21, 0x3ff
	s_ashr_i32 s4, s99, 31
	s_lshr_b32 s4, s4, 26
	s_add_i32 s4, s99, s4
	s_ashr_i32 s5, s4, 6
	s_andn2_b32 s4, s4, 63
	s_sub_i32 s6, s99, s4
	s_lshl_b32 s4, s5, 4
	s_and_b32 s5, s6, 15
	s_or_b32 s4, s5, s4
	s_ashr_i32 s6, s6, 4
	s_ashr_i32 s5, s4, 31
	s_ashr_i32 s7, s6, 31
	s_lshl_b64 s[10:11], s[4:5], 18
	s_lshl_b64 s[38:39], s[6:7], 18

; DI void glds16(const void* g, unsigned char* l) { __builtin_amdgcn_global_load_lds((const unsigned*)g, (lds_u32*)l, 16, 0, 0); }
;     ...
;   const int srow = tid >> 3, kch = (tid & 7) ^ ((tid >> 4) & 7);
;   const unsigned voA = (unsigned)(srow * lda + kch * 8) * 2u, voB = (unsigned)(srow * ldb + kch * 8) * 2u;
;   const char* Ab = (const char*)A;
;   const char* Bb = (const char*)B;
;   const int nk = K >> 6;
;   if (!primed) {
; #pragma unroll
;     for (int i = 0; i < NA; ++i) glds16(Ab + (size_t)i * 128 * lda + voA, smem + (i * 512 + tid) * 16);
; #pragma unroll
;     for (int i = 0; i < NB; ++i) glds16(Bb + (size_t)i * 128 * ldb + voB, smem + AB + (i * 512 + tid) * 16);
;   }
; DI void phase_gemm_resid(const bf16_t* __restrict__ A, int K, const bf16_t* __restrict__ Bt, const float* __restrict__ xin, float* __restrict__ xout, float alpha, unsigned char* smem) {
;     ...
;   for (int id = blockIdx.x; id < nM * nN; id += gridDim.x) {
;     int pm, pn; tile_coords(id, nN, pm, pn);
;     f32x4 acc[8][4]; zero_acc(acc);
;     {
;       const int idn = id + gridDim.x; int pm2 = 0, pn2 = 0; const bool hn = idn < nM * nN; if (hn) tile_coords(idn, nN, pm2, pn2);
;       gemm_block<8, 4, 2, 4>(A + (size_t)pm * 256 * K, K, Bt + (size_t)pn * 256 * K, K, K, acc, smem, id != (int)blockIdx.x,
;                              hn ? A + (size_t)pm2 * 256 * K : nullptr, K, Bt + (size_t)pn2 * 256 * K, K);
.LBB0_764:
	s_xor_b32 s99, s2, 0x3ff
	s_ashr_i32 s4, s99, 31
	s_lshr_b32 s4, s4, 26
	s_add_i32 s4, s99, s4
	s_ashr_i32 s5, s4, 6
	s_andn2_b32 s4, s4, 63
	v_lshrrev_b32_e32 v4, 4, v0
	s_sub_i32 s6, s99, s4
	v_xor_b32_e32 v3, v4, v0
	s_lshl_b32 s2, s5, 4
	s_and_b32 s22, s6, 15
	s_ashr_i32 s6, s6, 4
	v_lshlrev_b32_e32 v2, 8, v0
	v_lshlrev_b32_e32 v3, 4, v3
	s_or_b32 s4, s22, s2
	s_ashr_i32 s7, s6, 31
	v_and_b32_e32 v2, 0xfffff800, v2
	v_and_b32_e32 v3, 0x70, v3
	s_ashr_i32 s5, s4, 31
	s_lshl_b64 s[14:15], s[6:7], 19
	v_or_b32_e32 v128, v3, v2
	s_andn2_b64 vcc, exec, s[16:17]
	s_cbranch_vccnz .LBB0_766
	s_lshl_b64 s[16:17], s[4:5], 19
	s_add_u32 s16, s52, s16
	s_addc_u32 s17, s53, s17
	v_readfirstlane_b32 s7, v1
	v_add_u32_e32 v5, 0x2000, v1
	v_lshl_add_u64 v[6:7], s[16:17], 0, v[128:129]
	s_mov_b32 m0, s7
	v_readfirstlane_b32 s7, v5
	v_add_u32_e32 v5, 0x4000, v1
	global_load_lds_dwordx4 v[6:7], off
	v_lshl_add_u64 v[8:9], v[6:7], 0, s[70:71]
	s_mov_b32 m0, s7
	v_readfirstlane_b32 s7, v5
	v_add_u32_e32 v5, 0x6000, v1
	s_add_u32 s26, s8, s14
	global_load_lds_dwordx4 v[8:9], off
	v_lshl_add_u64 v[8:9], v[6:7], 0, s[80:81]
	s_mov_b32 m0, s7
	v_readfirstlane_b32 s7, v5
	v_add_u32_e32 v5, 0x8000, v1
	s_addc_u32 s27, s18, s15
	global_load_lds_dwordx4 v[8:9], off
	v_lshl_add_u64 v[6:7], v[6:7], 0, s[82:83]
	s_mov_b32 m0, s7
	v_readfirstlane_b32 s7, v5
	v_add_u32_e32 v5, 0xa000, v1
	global_load_lds_dwordx4 v[6:7], off
	v_lshl_add_u64 v[6:7], s[26:27], 0, v[128:129]
	s_mov_b32 m0, s7
	v_readfirstlane_b32 s7, v5
	v_add_u32_e32 v5, 0xc000, v1
	global_load_lds_dwordx4 v[6:7], off
	v_lshl_add_u64 v[8:9], v[6:7], 0, s[70:71]
	s_mov_b32 m0, s7
	v_readfirstlane_b32 s7, v5
	v_add_u32_e32 v5, 0xe000, v1
	global_load_lds_dwordx4 v[8:9], off
	v_lshl_add_u64 v[8:9], v[6:7], 0, s[80:81]
	s_mov_b32 m0, s7
	v_readfirstlane_b32 s7, v5
	global_load_lds_dwordx4 v[8:9], off
	v_lshl_add_u64 v[6:7], v[6:7], 0, s[82:83]
	s_mov_b32 m0, s7
	v_mov_b32_e32 v133, v1
	global_load_lds_dwordx4 v[6:7], off

; DI void phase_gemm_resid(const bf16_t* __restrict__ A, int K, const bf16_t* __restrict__ Bt, const float* __restrict__ xin, float* __restrict__ xout, float alpha, unsigned char* smem) {
;     ...
;   for (int id = blockIdx.x; id < nM * nN; id += gridDim.x) {
;     int pm, pn; tile_coords(id, nN, pm, pn);
;     f32x4 acc[8][4]; zero_acc(acc);
;     {
;       const int idn = id + gridDim.x; int pm2 = 0, pn2 = 0; const bool hn = idn < nM * nN; if (hn) tile_coords(idn, nN, pm2, pn2);
;       gemm_block<8, 4, 2, 4>(A + (size_t)pm * 256 * K, K, Bt + (size_t)pn * 256 * K, K, K, acc, smem, id != (int)blockIdx.x,
;                              hn ? A + (size_t)pm2 * 256 * K : nullptr, K, Bt + (size_t)pn2 * 256 * K, K);
.LBB0_960:
	v_readlane_b32 s4, v252, 0
	v_readlane_b32 s6, v252, 2
	s_add_i32 s21, s2, s6
	s_cmpk_gt_i32 s21, 0x3ff
	v_readlane_b32 s7, v252, 3
	s_cselect_b64 s[0:1], -1, 0
	s_cmpk_lt_i32 s21, 0x400
	s_cselect_b64 s[6:7], -1, 0
	s_mov_b64 s[12:13], 0
	s_and_b64 vcc, exec, s[0:1]
	s_mov_b64 s[10:11], 0
	v_readlane_b32 s5, v252, 1
	s_cbranch_vccnz .LBB0_962
	s_xor_b32 s99, s21, 0x3ff
	s_ashr_i32 s4, s99, 31
	s_lshr_b32 s4, s4, 26
	s_add_i32 s4, s99, s4
	s_ashr_i32 s5, s4, 6
	s_andn2_b32 s4, s4, 63
	s_sub_i32 s4, s99, s4
	s_lshl_b32 s5, s5, 4
	s_and_b32 s10, s4, 15
	s_lshr_b32 s4, s4, 4
	s_or_b32 s5, s10, s5
	s_mul_i32 s10, s4, 0xb0000
	s_mul_hi_i32 s13, s5, 0xb0000
	s_mul_i32 s12, s5, 0xb0000
	s_ashr_i32 s11, s10, 31

; DI void glds16(const void* g, unsigned char* l) { __builtin_amdgcn_global_load_lds((const unsigned*)g, (lds_u32*)l, 16, 0, 0); }
;     ...
;   const int srow = tid >> 3, kch = (tid & 7) ^ ((tid >> 4) & 7);
;   const unsigned voA = (unsigned)(srow * lda + kch * 8) * 2u, voB = (unsigned)(srow * ldb + kch * 8) * 2u;
;   const char* Ab = (const char*)A;
;   const char* Bb = (const char*)B;
;   const int nk = K >> 6;
;   if (!primed) {
; #pragma unroll
;     for (int i = 0; i < NA; ++i) glds16(Ab + (size_t)i * 128 * lda + voA, smem + (i * 512 + tid) * 16);
; #pragma unroll
;     for (int i = 0; i < NB; ++i) glds16(Bb + (size_t)i * 128 * ldb + voB, smem + AB + (i * 512 + tid) * 16);
;   }
; DI void phase_gemm_resid(const bf16_t* __restrict__ A, int K, const bf16_t* __restrict__ Bt, const float* __restrict__ xin, float* __restrict__ xout, float alpha, unsigned char* smem) {
;     ...
;   for (int id = blockIdx.x; id < nM * nN; id += gridDim.x) {
;     int pm, pn; tile_coords(id, nN, pm, pn);
;     f32x4 acc[8][4]; zero_acc(acc);
;     {
;       const int idn = id + gridDim.x; int pm2 = 0, pn2 = 0; const bool hn = idn < nM * nN; if (hn) tile_coords(idn, nN, pm2, pn2);
;       gemm_block<8, 4, 2, 4>(A + (size_t)pm * 256 * K, K, Bt + (size_t)pn * 256 * K, K, K, acc, smem, id != (int)blockIdx.x,
;                              hn ? A + (size_t)pm2 * 256 * K : nullptr, K, Bt + (size_t)pn2 * 256 * K, K);
.LBB0_964:
	s_xor_b32 s99, s2, 0x3ff
	s_ashr_i32 s4, s99, 31
	s_lshr_b32 s4, s4, 26
	s_add_i32 s4, s99, s4
	s_ashr_i32 s5, s4, 6
	s_andn2_b32 s4, s4, 63
	v_lshrrev_b32_e32 v4, 4, v0
	s_sub_i32 s2, s99, s4
	v_ashrrev_i32_e32 v2, 3, v0
	v_xor_b32_e32 v3, v4, v0
	s_movk_i32 s26, 0xb00
	s_lshl_b32 s22, s5, 4
	s_and_b32 s23, s2, 15
	s_ashr_i32 s2, s2, 4
	v_mul_lo_u32 v5, v2, s26
	v_lshlrev_b32_e32 v6, 3, v3
	s_or_b32 s4, s23, s22
	s_mul_i32 s14, s2, 0xb0000
	v_and_or_b32 v5, v6, 56, v5
	s_ashr_i32 s5, s4, 31
	s_ashr_i32 s15, s14, 31
	s_andn2_b64 vcc, exec, s[16:17]
	v_lshlrev_b32_e32 v128, 1, v5
	s_cbranch_vccnz .LBB0_966
	s_mul_i32 s16, s4, 0x160000
	s_mul_hi_i32 s17, s4, 0x160000
	s_add_u32 s16, s52, s16
	s_addc_u32 s17, s53, s17
	v_lshl_add_u64 v[6:7], s[16:17], 0, v[128:129]
	v_readfirstlane_b32 s16, v1
	v_add_u32_e32 v5, 0x2000, v1
	s_mov_b32 m0, s16
	s_mov_b64 s[38:39], 0x58000
	v_readfirstlane_b32 s16, v5
	v_add_u32_e32 v5, 0x4000, v1
	s_lshl_b64 s[26:27], s[14:15], 1
	global_load_lds_dwordx4 v[6:7], off
	v_lshl_add_u64 v[8:9], v[6:7], 0, s[38:39]
	s_mov_b32 m0, s16
	s_mov_b64 s[42:43], 0xb0000
	v_readfirstlane_b32 s16, v5
	v_add_u32_e32 v5, 0x6000, v1
	s_add_u32 s26, s8, s26
	global_load_lds_dwordx4 v[8:9], off
	v_lshl_add_u64 v[8:9], v[6:7], 0, s[42:43]
	s_mov_b32 m0, s16
	s_mov_b64 s[44:45], 0x108000
	v_readfirstlane_b32 s16, v5
	v_add_u32_e32 v5, 0x8000, v1
	s_addc_u32 s27, s18, s27
	global_load_lds_dwordx4 v[8:9], off
	v_lshl_add_u64 v[6:7], v[6:7], 0, s[44:45]
	s_mov_b32 m0, s16
	v_readfirstlane_b32 s16, v5
	v_add_u32_e32 v5, 0xa000, v1
	global_load_lds_dwordx4 v[6:7], off
	v_lshl_add_u64 v[6:7], s[26:27], 0, v[128:129]
	s_mov_b32 m0, s16
	v_readfirstlane_b32 s16, v5
	v_add_u32_e32 v5, 0xc000, v1
	global_load_lds_dwordx4 v[6:7], off
	v_lshl_add_u64 v[8:9], v[6:7], 0, s[38:39]
	s_mov_b32 m0, s16
	v_readfirstlane_b32 s16, v5
	v_add_u32_e32 v5, 0xe000, v1
	global_load_lds_dwordx4 v[8:9], off
	v_lshl_add_u64 v[8:9], v[6:7], 0, s[42:43]
	s_mov_b32 m0, s16
	v_readfirstlane_b32 s16, v5
	global_load_lds_dwordx4 v[8:9], off
	v_lshl_add_u64 v[6:7], v[6:7], 0, s[44:45]
	s_mov_b32 m0, s16
	v_mov_b32_e32 v133, v1
	global_load_lds_dwordx4 v[6:7], off
